# stack without the idle-secondary policy: trimmed scan loops + hoisted constants + mod_unit rewrites + leaner GEMM DMA issue blocks
# baseline (speedup 1.0000x reference)
.LBB0_136:
	s_andn2_b64 vcc, exec, s[14:15]
	s_cbranch_vccnz .LBB0_131
	s_add_i32 s14, s16, 0x8000
	s_and_b32 s14, s14, 0x8000
	v_add_u32_e32 v94, s14, v85
	v_lshl_add_u64 v[90:91], v[82:83], 0, s[28:29]
	v_readfirstlane_b32 s14, v94
	s_mov_b32 m0, s14
	v_lshl_add_u64 v[92:93], v[90:91], 0, s[50:51]
	s_mov_b64 s[14:15], 0x40000
	global_load_lds_dwordx4 v[92:93], off
	s_add_u32 m0, m0, 0x1000
	v_lshl_add_u64 v[92:93], v[92:93], 0, s[14:15]
	global_load_lds_dwordx4 v[92:93], off
	s_add_u32 m0, m0, 0x1000
	v_lshl_add_u64 v[92:93], v[92:93], 0, s[14:15]
	global_load_lds_dwordx4 v[92:93], off
	s_add_u32 m0, m0, 0x1000
	v_lshl_add_u64 v[92:93], v[92:93], 0, s[14:15]
	global_load_lds_dwordx4 v[92:93], off
	s_add_u32 m0, m0, 0x1000
	v_lshl_add_u64 v[90:91], v[80:81], 0, s[28:29]
	s_mov_b64 s[14:15], 0xa01080
	v_lshl_add_u64 v[92:93], v[90:91], 0, s[14:15]
	s_mov_b64 s[14:15], 0x40000
	global_load_lds_dwordx4 v[92:93], off
	s_add_u32 m0, m0, 0x1000
	v_lshl_add_u64 v[92:93], v[92:93], 0, s[14:15]
	global_load_lds_dwordx4 v[92:93], off
	s_add_u32 m0, m0, 0x1000
	v_lshl_add_u64 v[92:93], v[92:93], 0, s[14:15]
	global_load_lds_dwordx4 v[92:93], off
	s_add_u32 m0, m0, 0x1000
	v_lshl_add_u64 v[92:93], v[92:93], 0, s[14:15]
	global_load_lds_dwordx4 v[92:93], off
	s_branch .LBB0_131

.LBB0_197:
	s_andn2_b64 vcc, exec, s[14:15]
	s_cbranch_vccnz .LBB0_192
	s_add_i32 s14, s16, 0x8000
	s_and_b32 s14, s14, 0x8000
	v_add_u32_e32 v94, s14, v85
	v_lshl_add_u64 v[90:91], v[80:81], 0, s[22:23]
	v_readfirstlane_b32 s14, v94
	s_mov_b32 m0, s14
	v_lshl_add_u64 v[92:93], v[90:91], 0, s[64:65]
	s_mov_b64 s[14:15], 0x10000
	global_load_lds_dwordx4 v[92:93], off
	s_add_u32 m0, m0, 0x1000
	v_lshl_add_u64 v[92:93], v[92:93], 0, s[14:15]
	global_load_lds_dwordx4 v[92:93], off
	s_add_u32 m0, m0, 0x1000
	v_lshl_add_u64 v[92:93], v[92:93], 0, s[14:15]
	global_load_lds_dwordx4 v[92:93], off
	s_add_u32 m0, m0, 0x1000
	v_lshl_add_u64 v[92:93], v[92:93], 0, s[14:15]
	global_load_lds_dwordx4 v[92:93], off
	s_add_u32 m0, m0, 0x1000
	v_lshl_add_u64 v[90:91], v[82:83], 0, s[22:23]
	s_mov_b64 s[14:15], 0x201080
	v_lshl_add_u64 v[92:93], v[90:91], 0, s[14:15]
	s_mov_b64 s[14:15], 0x10000
	global_load_lds_dwordx4 v[92:93], off
	s_add_u32 m0, m0, 0x1000
	v_lshl_add_u64 v[92:93], v[92:93], 0, s[14:15]
	global_load_lds_dwordx4 v[92:93], off
	s_add_u32 m0, m0, 0x1000
	v_lshl_add_u64 v[92:93], v[92:93], 0, s[14:15]
	global_load_lds_dwordx4 v[92:93], off
	s_add_u32 m0, m0, 0x1000
	v_lshl_add_u64 v[92:93], v[92:93], 0, s[14:15]
	global_load_lds_dwordx4 v[92:93], off
	s_branch .LBB0_192

.LBB0_269:
	s_andn2_b64 vcc, exec, s[14:15]
	s_cbranch_vccnz .LBB0_264
	s_add_i32 s14, s16, 0x8000
	s_and_b32 s14, s14, 0x8000
	v_add_u32_e32 v94, s14, v84
	v_lshl_add_u64 v[90:91], v[82:83], 0, s[40:41]
	v_readfirstlane_b32 s14, v94
	s_mov_b32 m0, s14
	s_mov_b64 s[14:15], 0x86c1080
	v_lshl_add_u64 v[92:93], v[90:91], 0, s[14:15]
	s_mov_b64 s[14:15], 0x10000
	global_load_lds_dwordx4 v[92:93], off
	s_add_u32 m0, m0, 0x1000
	v_lshl_add_u64 v[92:93], v[92:93], 0, s[14:15]
	global_load_lds_dwordx4 v[92:93], off
	s_add_u32 m0, m0, 0x1000
	v_lshl_add_u64 v[92:93], v[92:93], 0, s[14:15]
	global_load_lds_dwordx4 v[92:93], off
	s_add_u32 m0, m0, 0x1000
	v_lshl_add_u64 v[92:93], v[92:93], 0, s[14:15]
	global_load_lds_dwordx4 v[92:93], off
	s_add_u32 m0, m0, 0x1000
	v_lshl_add_u64 v[90:91], v[80:81], 0, s[40:41]
	s_mov_b64 s[14:15], 0x2241080
	v_lshl_add_u64 v[92:93], v[90:91], 0, s[14:15]
	s_mov_b64 s[14:15], 0x10000
	global_load_lds_dwordx4 v[92:93], off
	s_add_u32 m0, m0, 0x1000
	v_lshl_add_u64 v[92:93], v[92:93], 0, s[14:15]
	global_load_lds_dwordx4 v[92:93], off
	s_add_u32 m0, m0, 0x1000
	v_lshl_add_u64 v[92:93], v[92:93], 0, s[14:15]
	global_load_lds_dwordx4 v[92:93], off
	s_add_u32 m0, m0, 0x1000
	v_lshl_add_u64 v[92:93], v[92:93], 0, s[14:15]
	global_load_lds_dwordx4 v[92:93], off
	s_branch .LBB0_264

.LBB0_337:
	s_andn2_b64 vcc, exec, s[16:17]
	s_cbranch_vccnz .LBB0_334
	s_add_i32 s85, s84, 0x8000
	s_and_b32 s16, s85, 0x8000
	v_add_u32_e32 v89, s16, v84
	v_lshl_add_u64 v[90:91], v[80:81], 0, s[44:45]
	v_readfirstlane_b32 s16, v89
	s_mov_b32 m0, s16
	s_mov_b64 s[16:17], 0x4ac1080
	v_lshl_add_u64 v[92:93], v[90:91], 0, s[16:17]
	s_mov_b64 s[16:17], 0x8000
	global_load_lds_dwordx4 v[92:93], off
	s_add_u32 m0, m0, 0x1000
	v_lshl_add_u64 v[92:93], v[92:93], 0, s[16:17]
	global_load_lds_dwordx4 v[92:93], off
	s_add_u32 m0, m0, 0x1000
	v_lshl_add_u64 v[92:93], v[92:93], 0, s[16:17]
	global_load_lds_dwordx4 v[92:93], off
	s_add_u32 m0, m0, 0x1000
	v_lshl_add_u64 v[92:93], v[92:93], 0, s[16:17]
	global_load_lds_dwordx4 v[92:93], off
	s_add_u32 m0, m0, 0x1000
	v_lshl_add_u64 v[90:91], v[82:83], 0, s[44:45]
	s_mov_b64 s[16:17], 0x1941080
	v_lshl_add_u64 v[92:93], v[90:91], 0, s[16:17]
	s_mov_b64 s[16:17], 0x10000
	global_load_lds_dwordx4 v[92:93], off
	s_add_u32 m0, m0, 0x1000
	v_lshl_add_u64 v[92:93], v[92:93], 0, s[16:17]
	global_load_lds_dwordx4 v[92:93], off
	s_add_u32 m0, m0, 0x1000
	v_lshl_add_u64 v[92:93], v[92:93], 0, s[16:17]
	global_load_lds_dwordx4 v[92:93], off
	s_add_u32 m0, m0, 0x1000
	v_lshl_add_u64 v[92:93], v[92:93], 0, s[16:17]
	global_load_lds_dwordx4 v[92:93], off
	s_branch .LBB0_334

.LBB0_342:
	s_andn2_b64 vcc, exec, s[16:17]
	s_cbranch_vccnz .LBB0_344
	s_add_i32 s85, s84, 0x8000
	s_and_b32 s16, s85, 0x8000
	v_add_u32_e32 v89, s16, v88
	v_lshl_add_u64 v[90:91], v[82:83], 0, s[44:45]
	v_readfirstlane_b32 s16, v89
	s_mov_b32 m0, s16
	s_mov_b64 s[16:17], 0xf8c1080
	v_lshl_add_u64 v[92:93], v[90:91], 0, s[16:17]
	s_mov_b64 s[16:17], 0x8000
	global_load_lds_dwordx4 v[92:93], off
	s_add_u32 m0, m0, 0x1000
	v_lshl_add_u64 v[92:93], v[92:93], 0, s[16:17]
	global_load_lds_dwordx4 v[92:93], off
	s_add_u32 m0, m0, 0x1000
	v_lshl_add_u64 v[92:93], v[92:93], 0, s[16:17]
	global_load_lds_dwordx4 v[92:93], off
	s_add_u32 m0, m0, 0x1000
	v_lshl_add_u64 v[92:93], v[92:93], 0, s[16:17]
	global_load_lds_dwordx4 v[92:93], off
	s_add_u32 m0, m0, 0x1000
	v_lshl_add_u64 v[90:91], v[80:81], 0, s[44:45]
	s_mov_b64 s[16:17], 0x1941480
	v_lshl_add_u64 v[92:93], v[90:91], 0, s[16:17]
	s_mov_b64 s[16:17], 0x10000
	global_load_lds_dwordx4 v[92:93], off
	s_add_u32 m0, m0, 0x1000
	v_lshl_add_u64 v[92:93], v[92:93], 0, s[16:17]
	global_load_lds_dwordx4 v[92:93], off
	s_add_u32 m0, m0, 0x1000
	v_lshl_add_u64 v[92:93], v[92:93], 0, s[16:17]
	global_load_lds_dwordx4 v[92:93], off
	s_add_u32 m0, m0, 0x1000
	v_lshl_add_u64 v[92:93], v[92:93], 0, s[16:17]
	global_load_lds_dwordx4 v[92:93], off

.LBB0_550:
	s_andn2_b64 vcc, exec, s[14:15]
	s_cbranch_vccnz .LBB0_545
	s_add_i32 s14, s16, 0x8000
	s_and_b32 s14, s14, 0x8000
	v_add_u32_e32 v94, s14, v85
	v_lshl_add_u64 v[90:91], v[82:83], 0, s[8:9]
	v_readfirstlane_b32 s14, v94
	s_mov_b32 m0, s14
	v_lshl_add_u64 v[92:93], v[90:91], 0, s[64:65]
	s_mov_b64 s[14:15], 0x10000
	global_load_lds_dwordx4 v[92:93], off
	s_add_u32 m0, m0, 0x1000
	v_lshl_add_u64 v[92:93], v[92:93], 0, s[14:15]
	global_load_lds_dwordx4 v[92:93], off
	s_add_u32 m0, m0, 0x1000
	v_lshl_add_u64 v[92:93], v[92:93], 0, s[14:15]
	global_load_lds_dwordx4 v[92:93], off
	s_add_u32 m0, m0, 0x1000
	v_lshl_add_u64 v[92:93], v[92:93], 0, s[14:15]
	global_load_lds_dwordx4 v[92:93], off
	s_add_u32 m0, m0, 0x1000
	v_lshl_add_u64 v[90:91], v[80:81], 0, s[8:9]
	v_lshl_add_u64 v[92:93], v[90:91], 0, s[50:51]
	s_mov_b64 s[14:15], 0x10000
	global_load_lds_dwordx4 v[92:93], off
	s_add_u32 m0, m0, 0x1000
	v_lshl_add_u64 v[92:93], v[92:93], 0, s[14:15]
	global_load_lds_dwordx4 v[92:93], off
	s_add_u32 m0, m0, 0x1000
	v_lshl_add_u64 v[92:93], v[92:93], 0, s[14:15]
	global_load_lds_dwordx4 v[92:93], off
	s_add_u32 m0, m0, 0x1000
	v_lshl_add_u64 v[92:93], v[92:93], 0, s[14:15]
	global_load_lds_dwordx4 v[92:93], off
	s_branch .LBB0_545
